# consistency check of the negm single-register save variant
# speedup vs baseline: 1.0017x; 1.0017x over previous
.LBB0_423:
	v_add_u32_e32 v81, s5, v206
	ds_read_b128 v[82:85], v81
	ds_read_b128 v[86:89], v81 offset:4096
	v_add_u32_e32 v90, s5, v207
	v_add_u32_e32 v94, s5, v208
	v_exp_f32_e32 v128, v128
	v_exp_f32_e32 v129, v129
	v_exp_f32_e32 v152, v96
	v_exp_f32_e32 v153, v97
	v_add_u32_e32 v81, s5, v209
	s_waitcnt lgkmcnt(1)
	v_mfma_f32_32x32x16_bf16 v[112:127], v[82:85], v[160:163], v[64:79]
	ds_read_b128 v[82:85], v90
	ds_read_b128 v[90:93], v90 offset:4096
	ds_read_b128 v[144:147], v94
	ds_read_b128 v[148:151], v94 offset:4096
	v_add_f32_e32 v154, v153, v152
	v_exp_f32_e32 v108, v108
	v_exp_f32_e32 v109, v109
	v_exp_f32_e32 v110, v110
	v_exp_f32_e32 v111, v111
	s_add_i32 s4, s4, 2
	s_waitcnt lgkmcnt(4)
	v_mfma_f32_32x32x16_bf16 v[64:79], v[86:89], v[160:163], v[64:79]
	ds_read_b128 v[86:89], v81
	ds_read_b128 v[94:97], v81 offset:4096
	v_add_f32_e32 v81, v129, v128
	v_add_f32_e32 v81, v154, v81
	v_add_f32_e32 v81, 0, v81
	v_cvt_pk_bf16_f32 v128, v128, v129
	s_add_i32 s5, s76, s77
	s_cmpk_eq_i32 s5, 0x2000
	s_waitcnt lgkmcnt(5)
	v_mfma_f32_32x32x16_bf16 v[112:127], v[82:85], v[164:167], v[112:127]
	v_exp_f32_e32 v83, v130
	v_exp_f32_e32 v84, v131
	v_exp_f32_e32 v85, v98
	v_exp_f32_e32 v98, v99
	v_exp_f32_e32 v99, v103
	v_cvt_pk_bf16_f32 v129, v83, v84
	v_exp_f32_e32 v103, v137
	s_waitcnt lgkmcnt(4)
	v_mfma_f32_32x32x16_bf16 v[64:79], v[90:93], v[164:167], v[64:79]
	v_add_f32_e32 v90, v84, v83
	v_add_f32_e32 v91, v98, v85
	v_add_f32_e32 v90, v91, v90
	v_add_f32_e32 v81, v90, v81
	v_exp_f32_e32 v90, v132
	v_exp_f32_e32 v91, v133
	v_exp_f32_e32 v92, v100
	v_exp_f32_e32 v93, v101
	s_waitcnt lgkmcnt(3)
	v_mfma_f32_32x32x16_bf16 v[112:127], v[144:147], v[168:171], v[112:127]
	v_cvt_pk_bf16_f32 v83, v85, v98
	v_add_f32_e32 v84, v91, v90
	v_add_f32_e32 v85, v93, v92
	v_add_f32_e32 v84, v85, v84
	v_cvt_pk_bf16_f32 v130, v90, v91
	v_exp_f32_e32 v85, v134
	v_exp_f32_e32 v90, v135
	s_waitcnt lgkmcnt(2)
	v_mfma_f32_32x32x16_bf16 v[64:79], v[148:151], v[168:171], v[64:79]
	v_exp_f32_e32 v98, v102
	v_add_f32_e32 v81, v84, v81
	v_add_f32_e32 v91, v90, v85
	v_exp_f32_e32 v102, v136
	v_exp_f32_e32 v136, v104
	v_exp_f32_e32 v137, v105
	v_cvt_pk_bf16_f32 v84, v92, v93
	s_waitcnt lgkmcnt(1)
	v_mfma_f32_32x32x16_bf16 v[112:127], v[86:89], v[172:175], v[112:127]
	v_add_f32_e32 v86, v99, v98
	v_add_f32_e32 v86, v86, v91
	v_add_f32_e32 v81, v86, v81
	ds_read_b64_tr_b16 v[86:87], v213 offset:40960
	ds_read_b64_tr_b16 v[88:89], v213 offset:43008
	v_cvt_pk_bf16_f32 v131, v85, v90
	v_add_f32_e32 v104, v103, v102
	v_add_f32_e32 v105, v137, v136
	s_waitcnt lgkmcnt(2)
	v_mfma_f32_32x32x16_bf16 v[64:79], v[94:97], v[172:175], v[64:79]
	ds_read_b64_tr_b16 v[90:91], v214 offset:40960
	ds_read_b64_tr_b16 v[92:93], v214 offset:43008
	ds_read_b64_tr_b16 v[94:95], v213 offset:45056
	ds_read_b64_tr_b16 v[96:97], v213 offset:47104
	v_cvt_pk_bf16_f32 v85, v98, v99
	v_cvt_pk_bf16_f32 v82, v152, v153
	s_cselect_b32 s8, s71, 0x2000
	s_cmpk_lg_i32 s5, 0x6000
	s_cselect_b32 s77, s8, 0
	s_add_u32 s38, s38, 0x40000
	s_waitcnt lgkmcnt(2)
	v_mfma_f32_32x32x16_bf16 v[32:47], v[90:93], v[128:131], v[32:47]
	v_add_f32_e32 v90, v105, v104
	v_add_f32_e32 v81, v90, v81
	v_cvt_pk_bf16_f32 v90, v102, v103
	v_exp_f32_e32 v91, v138
	v_exp_f32_e32 v92, v139
	v_exp_f32_e32 v138, v106
	v_exp_f32_e32 v106, v140
	v_mfma_f32_32x32x16_bf16 v[48:63], v[86:89], v[128:131], v[48:63]
	ds_read_b64_tr_b16 v[86:87], v215 offset:40960
	ds_read_b64_tr_b16 v[88:89], v215 offset:43008
	ds_read_b64_tr_b16 v[98:99], v214 offset:45056
	ds_read_b64_tr_b16 v[100:101], v214 offset:47104
	ds_read_b64_tr_b16 v[102:103], v216 offset:40960
	ds_read_b64_tr_b16 v[104:105], v216 offset:43008
	ds_read_b64_tr_b16 v[132:133], v215 offset:45056
	ds_read_b64_tr_b16 v[134:135], v215 offset:47104
	v_exp_f32_e32 v139, v107
	v_mov_b64_e32 v[158:159], v[78:79]
	s_addc_u32 s39, s39, 0
	s_add_i32 s75, s75, 0x20000
	s_and_b64 vcc, exec, s[6:7]
	s_waitcnt lgkmcnt(2)
	v_mfma_f32_32x32x16_bf16 v[0:15], v[102:105], v[128:131], v[0:15]
	v_exp_f32_e32 v102, v141
	v_exp_f32_e32 v103, v142
	v_exp_f32_e32 v104, v143
	v_add_f32_e32 v105, v92, v91
	v_cvt_pk_bf16_f32 v91, v91, v92
	v_cvt_pk_bf16_f32 v92, v106, v102
	v_cvt_pk_bf16_f32 v93, v103, v104
	v_mfma_f32_32x32x16_bf16 v[16:31], v[86:89], v[128:131], v[16:31]
	ds_read_b64_tr_b16 v[86:87], v216 offset:45056
	ds_read_b64_tr_b16 v[88:89], v216 offset:47104
	v_mov_b64_e32 v[156:157], v[76:77]
	v_mov_b64_e32 v[154:155], v[74:75]
	v_mov_b64_e32 v[152:153], v[72:73]
	v_mov_b64_e32 v[150:151], v[70:71]
	v_mov_b64_e32 v[148:149], v[68:69]
	v_mov_b64_e32 v[146:147], v[66:67]
	v_mfma_f32_32x32x16_bf16 v[48:63], v[94:97], v[90:93], v[48:63]
	v_add_f32_e32 v94, v139, v138
	v_add_f32_e32 v94, v94, v105
	v_add_f32_e32 v81, v94, v81
	v_add_f32_e32 v94, v102, v106
	v_add_f32_e32 v95, v109, v108
	v_add_f32_e32 v94, v95, v94
	v_add_f32_e32 v81, v94, v81
	v_mfma_f32_32x32x16_bf16 v[32:47], v[98:101], v[90:93], v[32:47]
	v_add_f32_e32 v94, v104, v103
	v_add_f32_e32 v95, v111, v110
	v_add_f32_e32 v94, v95, v94
	v_add_f32_e32 v106, v94, v81
	v_max_f32_e32 v81, v113, v113
	v_max_f32_e32 v94, v112, v112
	v_max_f32_e32 v81, v94, v81
	s_waitcnt lgkmcnt(2)
	v_mfma_f32_32x32x16_bf16 v[16:31], v[132:135], v[90:93], v[16:31]
	ds_read_b64_tr_b16 v[94:95], v213 offset:49152
	ds_read_b64_tr_b16 v[96:97], v213 offset:51200
	v_max3_f32 v81, v81, v114, v115
	v_max3_f32 v81, v81, v116, v117
	v_max3_f32 v81, v81, v118, v119
	v_max3_f32 v81, v81, v120, v121
	v_max3_f32 v81, v81, v122, v123
	v_max3_f32 v81, v81, v124, v125
	s_waitcnt lgkmcnt(2)
	v_mfma_f32_32x32x16_bf16 v[0:15], v[86:89], v[90:93], v[0:15]
	ds_read_b64_tr_b16 v[86:87], v214 offset:49152
	ds_read_b64_tr_b16 v[88:89], v214 offset:51200
	ds_read_b64_tr_b16 v[90:91], v213 offset:53248
	ds_read_b64_tr_b16 v[92:93], v213 offset:55296
	v_max3_f32 v81, v81, v126, v127
	v_max3_f32 v81, v81, v64, v65
	v_max3_f32 v81, v81, v66, v67
	v_max3_f32 v81, v81, v68, v69
	v_max3_f32 v81, v81, v70, v71
	v_max3_f32 v81, v81, v72, v73
	s_waitcnt lgkmcnt(4)
	v_mfma_f32_32x32x16_bf16 v[48:63], v[94:97], v[82:85], v[48:63]
	ds_read_b64_tr_b16 v[94:95], v215 offset:49152
	ds_read_b64_tr_b16 v[96:97], v215 offset:51200
	ds_read_b64_tr_b16 v[98:99], v214 offset:53248
	ds_read_b64_tr_b16 v[100:101], v214 offset:55296
	v_max3_f32 v81, v81, v74, v75
	v_max3_f32 v81, v81, v76, v77
	v_max3_f32 v107, v81, v78, v79
	v_pk_add_f32 v[196:197], v[194:195], v[106:107]
	v_mov_b64_e32 v[144:145], v[64:65]
	v_mov_b32_e32 v64, v80
	s_waitcnt lgkmcnt(6)
	v_mfma_f32_32x32x16_bf16 v[32:47], v[86:89], v[82:85], v[32:47]
	ds_read_b64_tr_b16 v[86:87], v216 offset:49152
	ds_read_b64_tr_b16 v[88:89], v216 offset:51200
	ds_read_b64_tr_b16 v[102:103], v215 offset:53248
	ds_read_b64_tr_b16 v[104:105], v215 offset:55296
	v_mov_b32_e32 v65, v80
	v_mov_b32_e32 v66, v80
	v_mov_b32_e32 v67, v80
	v_mov_b32_e32 v68, v80
	v_mov_b32_e32 v69, v80
	v_mov_b32_e32 v70, v80
	s_waitcnt lgkmcnt(6)
	v_mfma_f32_32x32x16_bf16 v[16:31], v[94:97], v[82:85], v[16:31]
	ds_read_b64_tr_b16 v[94:95], v216 offset:53248
	ds_read_b64_tr_b16 v[96:97], v216 offset:55296
	s_waitcnt vmcnt(0)
	v_mov_b32_e32 v71, v80
	v_mov_b32_e32 v72, v80
	v_mov_b32_e32 v73, v80
	v_mov_b32_e32 v74, v80
	v_mov_b32_e32 v75, v80
	s_waitcnt lgkmcnt(4)
	v_mfma_f32_32x32x16_bf16 v[0:15], v[86:89], v[82:85], v[0:15]
	v_cvt_pk_bf16_f32 v85, v110, v111
	v_cvt_pk_bf16_f32 v84, v108, v109
	v_cvt_pk_bf16_f32 v83, v138, v139
	v_cvt_pk_bf16_f32 v82, v136, v137
	v_mov_b32_e32 v76, v80
	v_mov_b32_e32 v77, v80
	v_mov_b32_e32 v78, v80
	v_mfma_f32_32x32x16_bf16 v[48:63], v[90:93], v[82:85], v[48:63]
	v_mov_b32_e32 v79, v80
	s_waitcnt lgkmcnt(0)
	s_barrier
	v_mfma_f32_32x32x16_bf16 v[32:47], v[98:101], v[82:85], v[32:47]
	v_mfma_f32_32x32x16_bf16 v[16:31], v[102:105], v[82:85], v[16:31]
	v_mfma_f32_32x32x16_bf16 v[0:15], v[94:97], v[82:85], v[0:15]
	s_cbranch_vccnz .LBB0_432

.LBB0_427:
	s_or_b64 exec, exec, s[8:9]
	v_mov_b32_e32 v80, v79
	v_mov_b64_e32 v[64:65], v[82:83]
	v_mov_b64_e32 v[66:67], v[84:85]
	v_mov_b64_e32 v[68:69], v[86:87]
	v_mov_b64_e32 v[70:71], v[88:89]
	v_mov_b64_e32 v[72:73], v[90:91]
	v_mov_b64_e32 v[74:75], v[92:93]
	v_mov_b64_e32 v[76:77], v[94:95]
	v_mov_b64_e32 v[78:79], v[96:97]
	s_branch .LBB0_429
.LBB0_428:
	v_mov_b32_e32 v80, v79
.LBB0_429:
	s_add_i32 s8, s76, 0
	v_add_u32_e32 v86, s8, v206
	ds_read_b128 v[82:85], v86
	ds_read_b128 v[86:89], v86 offset:4096
	v_add_u32_e32 v90, s8, v207
	v_add_u32_e32 v94, s8, v208
	v_add_u32_e32 v194, s8, v209
	s_waitcnt lgkmcnt(1)
	v_mfma_f32_32x32x16_bf16 v[128:143], v[82:85], v[160:163], v[64:79]
	ds_read_b128 v[82:85], v90
	ds_read_b128 v[90:93], v90 offset:4096
	v_exp_f32_e32 v95, v112
	v_exp_f32_e32 v245, v113
	v_exp_f32_e32 v145, v145
	v_exp_f32_e32 v244, v115
	v_exp_f32_e32 v115, v149
	v_cvt_pk_bf16_f32 v112, v95, v245
	s_waitcnt lgkmcnt(2)
	v_mfma_f32_32x32x16_bf16 v[96:111], v[86:89], v[160:163], v[64:79]
	ds_read_b128 v[86:89], v94
	ds_read_b128 v[232:235], v94 offset:4096
	ds_read_b128 v[236:239], v194
	ds_read_b128 v[240:243], v194 offset:4096
	v_exp_f32_e32 v94, v114
	v_exp_f32_e32 v114, v117
	v_exp_f32_e32 v156, v156
	s_add_i32 s8, s77, s76
	v_cvt_pk_bf16_f32 v113, v94, v244
	s_cmpk_eq_i32 s8, 0x2000
	s_waitcnt lgkmcnt(5)
	v_mfma_f32_32x32x16_bf16 v[128:143], v[82:85], v[164:167], v[128:143]
	v_exp_f32_e32 v85, v144
	v_exp_f32_e32 v84, v146
	v_exp_f32_e32 v144, v147
	s_cselect_b32 s9, s71, 0x2000
	v_cvt_pk_bf16_f32 v82, v85, v145
	s_cmpk_lg_i32 s8, 0x6000
	s_cselect_b32 s76, s9, 0
	s_waitcnt lgkmcnt(4)
	v_mfma_f32_32x32x16_bf16 v[96:111], v[90:93], v[164:167], v[96:111]
	v_add_f32_e64 v90, v94, v244
	v_add_f32_e64 v91, v95, v245
	v_add_f32_e64 v92, v84, v144
	v_add_f32_e64 v93, v85, v145
	v_exp_f32_e32 v94, v120
	v_pk_add_f32 v[90:91], v[90:91], v[92:93]
	v_exp_f32_e32 v92, v116
	v_exp_f32_e32 v93, v148
	v_add_f32_e32 v83, 0, v91
	s_waitcnt lgkmcnt(3)
	v_mfma_f32_32x32x16_bf16 v[128:143], v[86:89], v[168:171], v[128:143]
	v_add_f32_e32 v87, v90, v83
	v_cvt_pk_bf16_f32 v83, v84, v144
	v_add_f32_e64 v84, v92, v114
	v_add_f32_e64 v85, v93, v115
	v_exp_f32_e32 v86, v119
	v_pk_add_f32 v[88:89], v[84:85], v[84:85] op_sel_hi:[0,1]
	v_exp_f32_e32 v85, v118
	v_exp_f32_e32 v88, v150
	v_exp_f32_e32 v90, v151
	s_waitcnt lgkmcnt(2)
	v_mfma_f32_32x32x16_bf16 v[96:111], v[232:235], v[168:171], v[96:111]
	v_cvt_pk_bf16_f32 v114, v92, v114
	v_cvt_pk_bf16_f32 v84, v93, v115
	v_add_f32_e32 v95, v85, v86
	v_add_f32_e32 v233, v88, v90
	v_cvt_pk_bf16_f32 v115, v85, v86
	v_cvt_pk_bf16_f32 v85, v88, v90
	ds_read_b64_tr_b16 v[90:91], v213 offset:24576
	ds_read_b64_tr_b16 v[92:93], v213 offset:26624
	v_exp_f32_e32 v232, v121
	v_exp_f32_e32 v88, v152
	v_exp_f32_e32 v86, v153
	ds_read_b64_tr_b16 v[116:117], v214 offset:24576
	ds_read_b64_tr_b16 v[118:119], v214 offset:26624
	ds_read_b64_tr_b16 v[144:145], v213 offset:28672
	ds_read_b64_tr_b16 v[146:147], v213 offset:30720
	v_pk_add_f32 v[120:121], v[94:95], v[232:233]
	s_waitcnt lgkmcnt(4)
	v_mfma_f32_32x32x16_bf16 v[48:63], v[90:93], v[112:115], v[48:63]
	v_add_f32_e64 v90, v88, v86
	v_add_f32_e64 v91, v89, v87
	v_exp_f32_e32 v234, v122
	v_pk_add_f32 v[152:153], v[120:121], v[90:91]
	ds_read_b64_tr_b16 v[90:91], v215 offset:24576
	ds_read_b64_tr_b16 v[92:93], v215 offset:26624
	ds_read_b64_tr_b16 v[148:149], v214 offset:28672
	ds_read_b64_tr_b16 v[150:151], v214 offset:30720
	v_exp_f32_e32 v235, v154
	v_exp_f32_e32 v87, v124
	v_exp_f32_e32 v89, v125
	v_mfma_f32_32x32x16_bf16 v[128:143], v[236:239], v[172:175], v[128:143]
	v_exp_f32_e32 v236, v123
	v_exp_f32_e32 v237, v155
	v_pk_add_f32 v[238:239], v[152:153], v[152:153] op_sel_hi:[0,1]
	v_exp_f32_e32 v238, v159
	s_min_u32 s8, s4, 32
	s_min_u32 s10, s4, 33
	s_lshl_b32 s8, s8, 17
	s_waitcnt lgkmcnt(6)
	v_mfma_f32_32x32x16_bf16 v[32:47], v[116:119], v[112:115], v[32:47]
	ds_read_b64_tr_b16 v[116:117], v216 offset:24576
	ds_read_b64_tr_b16 v[118:119], v216 offset:26624
	ds_read_b64_tr_b16 v[120:121], v215 offset:28672
	ds_read_b64_tr_b16 v[122:123], v215 offset:30720
	ds_read_b64_tr_b16 v[152:153], v216 offset:28672
	ds_read_b64_tr_b16 v[154:155], v216 offset:30720
	s_add_u32 s8, s36, s8
	s_addc_u32 s9, s37, 0
	s_waitcnt lgkmcnt(8)
	v_mfma_f32_32x32x16_bf16 v[16:31], v[90:93], v[112:115], v[16:31]
	v_add_f32_e64 v92, v234, v236
	v_add_f32_e64 v93, v235, v237
	v_cvt_pk_bf16_f32 v90, v94, v232
	v_add_f32_e64 v94, v92, v92
	v_add_f32_e64 v95, v92, v93
	v_cvt_pk_bf16_f32 v91, v234, v236
	v_cvt_pk_bf16_f32 v92, v87, v89
	v_exp_f32_e32 v94, v158
	s_waitcnt lgkmcnt(4)
	v_mfma_f32_32x32x16_bf16 v[0:15], v[116:119], v[112:115], v[0:15]
	v_exp_f32_e32 v112, v126
	v_exp_f32_e32 v114, v127
	v_add_f32_e32 v113, v87, v89
	v_max_f32_e32 v89, v128, v128
	v_cvt_pk_bf16_f32 v93, v112, v114
	s_nop 1
	v_mfma_f32_32x32x16_bf16 v[48:63], v[144:147], v[90:93], v[48:63]
	v_exp_f32_e32 v144, v157
	v_cvt_pk_bf16_f32 v147, v94, v238
	v_cvt_pk_bf16_f32 v145, v235, v237
	v_add_f32_e32 v115, v156, v144
	v_pk_add_f32 v[112:113], v[112:113], v[114:115]
	v_pk_add_f32 v[114:115], v[94:95], v[238:239]
	v_mfma_f32_32x32x16_bf16 v[32:47], v[148:151], v[90:93], v[32:47]
	v_add_f32_e64 v112, v112, v114
	v_add_f32_e64 v113, v113, v115
	v_cvt_pk_bf16_f32 v146, v156, v144
	v_add_f32_e32 v87, v112, v113
	ds_read_b64_tr_b16 v[112:113], v213 offset:32768
	ds_read_b64_tr_b16 v[114:115], v213 offset:34816
	v_add_f32_e32 v194, v196, v87
	v_max_f32_e32 v87, v129, v129
	v_max_f32_e32 v87, v89, v87
	s_waitcnt lgkmcnt(4)
	v_mfma_f32_32x32x16_bf16 v[16:31], v[120:123], v[90:93], v[16:31]
	v_max3_f32 v87, v87, v130, v131
	v_max3_f32 v87, v87, v132, v133
	v_max3_f32 v87, v87, v134, v135
	v_max3_f32 v87, v87, v136, v137
	v_max3_f32 v87, v87, v138, v139
	v_max3_f32 v87, v87, v140, v141
	v_max3_f32 v87, v87, v142, v143
	s_waitcnt lgkmcnt(2)
	v_mfma_f32_32x32x16_bf16 v[0:15], v[152:155], v[90:93], v[0:15]
	ds_read_b64_tr_b16 v[90:91], v214 offset:32768
	ds_read_b64_tr_b16 v[92:93], v214 offset:34816
	ds_read_b64_tr_b16 v[116:117], v213 offset:36864
	ds_read_b64_tr_b16 v[118:119], v213 offset:38912
	v_cvt_pk_bf16_f32 v144, v88, v86
	s_waitcnt lgkmcnt(4)
	v_mfma_f32_32x32x16_bf16 v[48:63], v[112:115], v[82:85], v[48:63]
	ds_read_b64_tr_b16 v[112:113], v215 offset:32768
	ds_read_b64_tr_b16 v[114:115], v215 offset:34816
	ds_read_b64_tr_b16 v[120:121], v214 offset:36864
	ds_read_b64_tr_b16 v[122:123], v214 offset:38912
	s_waitcnt lgkmcnt(6)
	v_mfma_f32_32x32x16_bf16 v[32:47], v[90:93], v[82:85], v[32:47]
	ds_read_b64_tr_b16 v[90:91], v216 offset:32768
	ds_read_b64_tr_b16 v[92:93], v216 offset:34816
	ds_read_b64_tr_b16 v[124:125], v215 offset:36864
	ds_read_b64_tr_b16 v[126:127], v215 offset:38912
	v_mfma_f32_32x32x16_bf16 v[96:111], v[240:243], v[172:175], v[96:111]
	s_waitcnt lgkmcnt(6)
	v_mfma_f32_32x32x16_bf16 v[16:31], v[112:115], v[82:85], v[16:31]
	ds_read_b64_tr_b16 v[112:113], v216 offset:36864
	ds_read_b64_tr_b16 v[114:115], v216 offset:38912
	s_nop 7
	v_max3_f32 v87, v87, v96, v97
	v_max3_f32 v87, v87, v98, v99
	s_waitcnt vmcnt(0)
	s_waitcnt lgkmcnt(0)
	s_barrier
	v_mfma_f32_32x32x16_bf16 v[0:15], v[90:93], v[82:85], v[0:15]
	v_lshl_add_u64 v[82:83], v[180:181], 1, s[8:9]
	s_add_i32 s8, s43, s76
	v_lshl_add_u64 v[82:83], v[82:83], 0, s[24:25]
	s_mov_b32 s9, m0
	s_mov_b32 m0, s8
	s_nop 0
	global_load_lds_dwordx4 v[82:83], off
	s_mov_b32 m0, s9
	s_lshl_b32 s8, s10, 17
	v_max3_f32 v87, v87, v100, v101
	s_add_u32 s8, s26, s8
	v_mfma_f32_32x32x16_bf16 v[48:63], v[116:119], v[144:147], v[48:63]
	v_max3_f32 v87, v87, v102, v103
	s_addc_u32 s9, s27, 0
	v_max3_f32 v87, v87, v104, v105
	s_add_u32 s8, s8, 0x40000
	v_max3_f32 v87, v87, v106, v107
	s_addc_u32 s9, s9, 0
	v_max3_f32 v87, v87, v108, v109
	v_mfma_f32_32x32x16_bf16 v[32:47], v[120:123], v[144:147], v[32:47]
	v_lshl_add_u64 v[82:83], v[176:177], 1, s[8:9]
	s_mov_b32 s10, m0
	s_mov_b32 m0, s65
	s_nop 0
	global_load_lds_dwordx4 v[82:83], off
	s_mov_b32 m0, s10
	v_max3_f32 v87, v87, v110, v111
	v_lshl_add_u64 v[82:83], v[178:179], 1, s[8:9]
	s_mov_b32 s8, m0
	s_mov_b32 m0, s66
	s_nop 0
	global_load_lds_dwordx4 v[82:83], off
	s_mov_b32 m0, s8
	v_add_f32_e32 v87, v195, v87
	v_cmp_gt_f32_e32 vcc, v87, v81
	v_mfma_f32_32x32x16_bf16 v[16:31], v[124:127], v[144:147], v[16:31]
	v_mfma_f32_32x32x16_bf16 v[0:15], v[112:115], v[144:147], v[0:15]
	s_cbranch_vccz .LBB0_423
	ds_bpermute_b32 v82, v204, v87
	v_max_f32_e32 v83, v87, v87
	s_waitcnt lgkmcnt(0)
	v_max_f32_e32 v82, v82, v82
	v_max_f32_e32 v112, v83, v82
	v_cmp_gt_f32_e32 vcc, v112, v81
	s_and_saveexec_b64 s[8:9], vcc
	s_cbranch_execz .LBB0_422
	v_sub_f32_e32 v65, v112, v195
	v_exp_f32_e64 v64, -v65
	v_xor_b32_e32 v80, 0x80000000, v112
	v_mov_b32_e32 v81, v80
	v_sub_f32_e32 v128, v128, v65
	v_mul_f32_e32 v194, v194, v64
	v_pk_mul_f32 v[62:63], v[62:63], v[64:65] op_sel_hi:[1,0]
	v_pk_mul_f32 v[60:61], v[60:61], v[64:65] op_sel_hi:[1,0]
	v_pk_mul_f32 v[58:59], v[58:59], v[64:65] op_sel_hi:[1,0]
	v_pk_mul_f32 v[56:57], v[56:57], v[64:65] op_sel_hi:[1,0]
	v_pk_mul_f32 v[54:55], v[54:55], v[64:65] op_sel_hi:[1,0]
	v_pk_mul_f32 v[52:53], v[52:53], v[64:65] op_sel_hi:[1,0]
	v_pk_mul_f32 v[50:51], v[50:51], v[64:65] op_sel_hi:[1,0]
	v_pk_mul_f32 v[48:49], v[48:49], v[64:65] op_sel_hi:[1,0]
	v_pk_mul_f32 v[46:47], v[46:47], v[64:65] op_sel_hi:[1,0]
	v_pk_mul_f32 v[44:45], v[44:45], v[64:65] op_sel_hi:[1,0]
	v_pk_mul_f32 v[42:43], v[42:43], v[64:65] op_sel_hi:[1,0]
	v_pk_mul_f32 v[40:41], v[40:41], v[64:65] op_sel_hi:[1,0]
	v_pk_mul_f32 v[38:39], v[38:39], v[64:65] op_sel_hi:[1,0]
	v_pk_mul_f32 v[36:37], v[36:37], v[64:65] op_sel_hi:[1,0]
	v_pk_mul_f32 v[34:35], v[34:35], v[64:65] op_sel_hi:[1,0]
	v_pk_mul_f32 v[32:33], v[32:33], v[64:65] op_sel_hi:[1,0]
	v_pk_mul_f32 v[30:31], v[30:31], v[64:65] op_sel_hi:[1,0]
	v_pk_mul_f32 v[28:29], v[28:29], v[64:65] op_sel_hi:[1,0]
	v_pk_mul_f32 v[26:27], v[26:27], v[64:65] op_sel_hi:[1,0]
	v_pk_mul_f32 v[24:25], v[24:25], v[64:65] op_sel_hi:[1,0]
	v_pk_mul_f32 v[22:23], v[22:23], v[64:65] op_sel_hi:[1,0]
	v_pk_mul_f32 v[20:21], v[20:21], v[64:65] op_sel_hi:[1,0]
	v_pk_mul_f32 v[18:19], v[18:19], v[64:65] op_sel_hi:[1,0]
	v_pk_mul_f32 v[16:17], v[16:17], v[64:65] op_sel_hi:[1,0]
	v_pk_mul_f32 v[14:15], v[14:15], v[64:65] op_sel_hi:[1,0]
	v_pk_mul_f32 v[12:13], v[12:13], v[64:65] op_sel_hi:[1,0]
	v_pk_mul_f32 v[10:11], v[10:11], v[64:65] op_sel_hi:[1,0]
	v_pk_mul_f32 v[8:9], v[8:9], v[64:65] op_sel_hi:[1,0]
	v_pk_mul_f32 v[6:7], v[6:7], v[64:65] op_sel_hi:[1,0]
	v_pk_mul_f32 v[4:5], v[4:5], v[64:65] op_sel_hi:[1,0]
	v_pk_mul_f32 v[2:3], v[2:3], v[64:65] op_sel_hi:[1,0]
	v_pk_mul_f32 v[0:1], v[0:1], v[64:65] op_sel_hi:[1,0]
	v_sub_f32_e32 v129, v129, v65
	v_sub_f32_e32 v130, v130, v65
	v_sub_f32_e32 v131, v131, v65
	v_sub_f32_e32 v132, v132, v65
	v_sub_f32_e32 v133, v133, v65
	v_sub_f32_e32 v134, v134, v65
	v_sub_f32_e32 v135, v135, v65
	v_sub_f32_e32 v136, v136, v65
	v_sub_f32_e32 v137, v137, v65
	v_sub_f32_e32 v138, v138, v65
	v_sub_f32_e32 v139, v139, v65
	v_sub_f32_e32 v140, v140, v65
	v_sub_f32_e32 v141, v141, v65
	v_sub_f32_e32 v142, v142, v65
	v_sub_f32_e32 v143, v143, v65
	v_sub_f32_e32 v96, v96, v65
	v_sub_f32_e32 v97, v97, v65
	v_sub_f32_e32 v98, v98, v65
	v_sub_f32_e32 v99, v99, v65
	v_sub_f32_e32 v100, v100, v65
	v_sub_f32_e32 v101, v101, v65
	v_sub_f32_e32 v102, v102, v65
	v_sub_f32_e32 v103, v103, v65
	v_sub_f32_e32 v104, v104, v65
	v_sub_f32_e32 v105, v105, v65
	v_sub_f32_e32 v106, v106, v65
	v_sub_f32_e32 v107, v107, v65
	v_sub_f32_e32 v108, v108, v65
	v_sub_f32_e32 v109, v109, v65
	v_sub_f32_e32 v110, v110, v65
	v_sub_f32_e32 v111, v111, v65
	v_mov_b32_e32 v82, v80
	v_mov_b32_e32 v83, v80
	v_mov_b32_e32 v84, v80
	v_mov_b32_e32 v85, v80
	v_mov_b32_e32 v86, v80
	v_mov_b32_e32 v87, v80
	v_mov_b32_e32 v88, v80
	v_mov_b32_e32 v89, v80
	v_mov_b32_e32 v90, v80
	v_mov_b32_e32 v91, v80
	v_mov_b32_e32 v92, v80
	v_mov_b32_e32 v93, v80
	v_mov_b32_e32 v94, v80
	v_mov_b32_e32 v95, v80
	v_mov_b64_e32 v[64:65], v[80:81]
	v_mov_b32_e32 v195, v112
	v_mov_b64_e32 v[66:67], v[82:83]
	v_mov_b64_e32 v[68:69], v[84:85]
	v_mov_b64_e32 v[70:71], v[86:87]
	v_mov_b64_e32 v[72:73], v[88:89]
	v_mov_b64_e32 v[74:75], v[90:91]
	v_mov_b64_e32 v[76:77], v[92:93]
	v_mov_b64_e32 v[78:79], v[94:95]
	s_branch .LBB0_422
